# first K-loop iteration after the G4 SwiGLU epilogue: first two DMA waits relaxed (no wait for epilogue store acks)
# baseline (speedup 1.0000x reference)
; #define PG8_STAGE(bufoff, gbase, voff) do { _Pragma("unroll") for (int _i = 0; _i < 2; ++_i) \
;         __builtin_amdgcn_global_load_lds((const unsigned*)((const char*)(gbase) + (voff)[_i]), (PG8_LAS unsigned*)(lds + (bufoff) + ldsw + _i * 8192), 16, 0, 0); } while (0)
; #define PG8_WAIT_V(n) asm volatile("s_waitcnt vmcnt(" #n ")" ::: "memory")
; #define PG8_BAR __builtin_amdgcn_s_barrier()
; template <class Epi, class Sched, bool ALIGN_EPI = false, bool SP2 = false>
; __device__ __forceinline__ void gemm_phase(PG8_LAS unsigned char* lds, const Gemm g, const Sched& S, const Epi& E) {
;     ...
;     for (int i = 0; i < 2; ++i) { int R, C; stage_rc(tid * 16 + i * 8192, R, C); const int Rb = Epi::PERM ? ((R & ~31) + perm32(R & 31)) : R;
;         voffA[i] = (unsigned)(R * K + C) * 2u; voffB[i] = (unsigned)(Rb * K + C) * 2u; }
;     const size_t kstep = (size_t)(BK * 2);
;     const size_t hstep = (size_t)HALF * K * 2;
;     const size_t tstep = 2 * hstep;
;     const unsigned ldsw = (unsigned)wid * 1024u;
;     const int aoff = lds_byte(wr * 64 + fr, fq * 8), boff = lds_byte(wc * 32 + fr, fq * 8);
;     ...
;         PG8_WAIT_V(2); PG8_BAR;
;         PG8_STAGE(PG8_SB(1, 0), cB + kstep, voffB); PG8_STAGE(PG8_SA(1, 0), cA + kstep, voffA); PG8_STAGE(PG8_SB(1, 1), cB + hstep + kstep, voffB);
;         PG8_WAIT_V(6); PG8_BAR;
.LBB0_38:
	v_lshrrev_b32_e32 v16, 1, v14
	v_and_b32_e32 v16, 24, v16
	v_and_b32_e32 v15, 15, v14
	v_lshlrev_b32_e32 v17, 1, v16
	v_lshlrev_b32_e32 v14, 2, v14
	s_sext_i32_i16 s0, s2
	v_lshl_or_b32 v152, s12, 6, v15
	v_lshl_or_b32 v15, v15, 6, v17
	s_lshl_b32 s2, s12, 13
	v_and_b32_e32 v14, 32, v14
	v_bitop3_b32 v17, v15, s2, v14 bitop3:0xde
	s_lshl_b32 s2, s3, 5
	s_and_b32 s12, s2, 0x60
	s_add_i32 m0, s68, 0x18000
	v_lshl_add_u64 v[6:7], v[6:7], 0, s[14:15]
	s_lshl_b32 s2, s12, 7
	s_waitcnt vmcnt(2)
	s_barrier
	global_load_lds_dwordx4 v[6:7], off
	v_lshl_add_u64 v[4:5], v[4:5], 0, s[14:15]
	s_add_i32 m0, s68, 0x1a000
	s_add_i32 s88, s68, 0x8000
	s_add_i32 s89, s68, 0xa000
	v_bitop3_b32 v153, v15, s2, v14 bitop3:0xde
	global_load_lds_dwordx4 v[4:5], off
	v_lshl_add_u64 v[0:1], v[0:1], 0, s[14:15]
	s_mov_b32 m0, s88
	s_add_u32 s2, s62, 0x40080
	global_load_lds_dwordx4 v[0:1], off
	v_lshl_add_u64 v[0:1], v[2:3], 0, s[14:15]
	s_mov_b32 m0, s89
	s_addc_u32 s3, s63, 0
	global_load_lds_dwordx4 v[0:1], off
	s_add_i32 m0, s68, 0x1c000
	v_lshl_add_u64 v[0:1], s[2:3], 0, v[132:133]
	global_load_lds_dwordx4 v[0:1], off
	v_lshl_add_u64 v[0:1], s[2:3], 0, v[128:129]
	s_add_i32 m0, s68, 0x1e000
	s_cmpk_lt_u32 s1, 0x100
	global_load_lds_dwordx4 v[0:1], off
	v_lshlrev_b32_e32 v0, 14, v12
	v_and_b32_e32 v0, 0xffff8000, v0
	v_lshl_add_u32 v0, v11, 11, v0
	v_and_b32_e32 v1, 1, v12
	v_lshl_or_b32 v0, v1, 6, v0
	v_lshl_add_u32 v142, v13, 1, v0
	v_lshlrev_b32_e32 v0, 14, v8
	v_and_b32_e32 v0, 0xffff8000, v0
	s_waitcnt vmcnt(0)
	v_lshl_add_u32 v0, v9, 11, v0
	v_and_b32_e32 v1, 1, v8
	v_lshl_or_b32 v0, v1, 6, v0
	s_cselect_b64 s[20:21], -1, 0
	s_ashr_i32 s90, s83, 31
	v_or_b32_e32 v154, s12, v16
	v_mov_b32_e32 v143, v133
	v_lshl_add_u32 v144, v10, 1, v0
	v_mov_b32_e32 v145, v133
	s_mov_b32 s91, 0
	v_add_u32_e32 v155, 0, v17
	s_barrier
	s_branch .LBB0_41

; #define PG8_STAGE(bufoff, gbase, voff) do { _Pragma("unroll") for (int _i = 0; _i < 2; ++_i) \
;         __builtin_amdgcn_global_load_lds((const unsigned*)((const char*)(gbase) + (voff)[_i]), (PG8_LAS unsigned*)(lds + (bufoff) + ldsw + _i * 8192), 16, 0, 0); } while (0)
; #define PG8_LDA(dst, b, h) do { _Pragma("unroll") for (int m = 0; m < 4; ++m) _Pragma("unroll") for (int k = 0; k < 2; ++k) dst[m][k] = *(const PG8_LAS bf16x8*)(lds + PG8_SA(b, h) + aoff + m * 2048 + k * 1024); } while (0)
; #define PG8_LDB(dst, b, h) do { _Pragma("unroll") for (int n = 0; n < 2; ++n) _Pragma("unroll") for (int k = 0; k < 2; ++k) dst[n][k] = *(const PG8_LAS bf16x8*)(lds + PG8_SB(b, h) + boff + n * 2048 + k * 1024); } while (0)
; #define PG8_WAIT_V(n) asm volatile("s_waitcnt vmcnt(" #n ")" ::: "memory")
; #define PG8_WAIT_L(n) asm volatile("s_waitcnt lgkmcnt(" #n ")" ::: "memory")
; #define PG8_BAR __builtin_amdgcn_s_barrier()
; #define PG8_SCHED __builtin_amdgcn_sched_barrier(0)
; template <class Epi, class Sched, bool ALIGN_EPI = false, bool SP2 = false>
; __device__ __forceinline__ void gemm_phase(PG8_LAS unsigned char* lds, const Gemm g, const Sched& S, const Epi& E) {
;     ...
;         const char* nA = has_next ? (const char*)g.A + (size_t)nxt.pm * tstep : cA; const char* nB = has_next ? (const char*)g.Bt + (size_t)nxt.pn * tstep : cB;
;         for (int t = 0; t < nt; t += 2) {
;             const bool last = (t == nt - 2);
;             const char* a1 = cA + (size_t)(t + 1) * kstep;
;             const char* a2 = last ? nA : cA + (size_t)(t + 2) * kstep; const char* b2 = last ? nB : cB + (size_t)(t + 2) * kstep;
;             const char* a3 = a2 + kstep; const char* b3 = b2 + kstep;
;             if (last && has_next) S.a_ready(nxt);
;             if constexpr (SP2) {
;             PG8_LDB(B0, 0, 0); PG8_LDB(B1, 0, 1); PG8_SCHED; PG8_LDA(At, 0, 0); PG8_STAGE(PG8_SA(1, 1), a1 + hstep, voffA);
;             PG8_WAIT_V(8); PG8_WAIT_L(0); PG8_BAR; PG8_MMA(0, 0, At, B0); PG8_MMA(0, 1, At, B1); PG8_BAR; PG8_SCHED;
;             PG8_LDA(At, 0, 1); PG8_STAGE(PG8_SB(0, 0), b2, voffB); PG8_STAGE(PG8_SB(0, 1), b2 + hstep, voffB); PG8_STAGE(PG8_SA(0, 0), a2, voffA);
;             PG8_WAIT_V(8); PG8_WAIT_L(0); PG8_BAR; PG8_MMA(1, 0, At, B0); PG8_MMA(1, 1, At, B1); PG8_BAR; PG8_SCHED;
.LBB0_43:
	s_ashr_i32 s47, s46, 31
	s_lshl_b64 s[24:25], s[46:47], 19
	s_add_u32 s48, s26, s24
	s_addc_u32 s49, s27, s25
	s_and_b64 s[24:25], s[40:41], exec
	s_cselect_b32 s1, s49, s61
	s_cselect_b32 s12, s48, s60
	s_ashr_i32 s3, s2, 31
	s_lshl_b64 s[24:25], s[2:3], 19
	s_add_u32 s56, s23, s24
	s_addc_u32 s57, s29, s25
	s_and_b64 s[24:25], s[40:41], exec
	s_cselect_b32 s3, s57, s63
	s_cselect_b32 s22, s56, s62
	s_add_u32 s60, s60, 0x40080
	s_addc_u32 s61, s61, 0
	s_add_u32 s33, s62, 0x100
	s_addc_u32 s44, s63, 0
	s_mov_b32 s45, -2
	s_add_u32 s24, s60, 0xfffc0080
	s_addc_u32 s25, s61, -1
	s_add_i32 s47, 0, 0x10000
	s_cmp_eq_u32 s45, 12
	s_cselect_b32 s65, s1, s25
	s_cselect_b32 s64, s12, s24
	v_add_u32_e32 v150, s47, v153
	s_cselect_b32 s63, s3, s44
	s_cselect_b32 s62, s22, s33
	s_add_i32 s50, 0, 0x14000
	ds_read_b128 v[146:149], v150
	ds_read_b128 v[156:159], v150 offset:1024
	ds_read_b128 v[160:163], v150 offset:2048
	ds_read_b128 v[164:167], v150 offset:3072
	v_add_u32_e32 v150, s50, v153
	ds_read_b128 v[168:171], v150
	ds_read_b128 v[192:195], v150 offset:1024
	ds_read_b128 v[196:199], v150 offset:2048
	ds_read_b128 v[200:203], v150 offset:3072
	v_lshl_add_u64 v[150:151], s[60:61], 0, v[142:143]
	s_add_i32 m0, s68, 0xc000
	ds_read_b128 v[204:207], v155
	ds_read_b128 v[208:211], v155 offset:1024
	ds_read_b128 v[212:215], v155 offset:2048
	ds_read_b128 v[216:219], v155 offset:3072
	ds_read_b128 v[220:223], v155 offset:4096
	ds_read_b128 v[224:227], v155 offset:5120
	ds_read_b128 v[228:231], v155 offset:6144
	ds_read_b128 v[232:235], v155 offset:7168
	global_load_lds_dwordx4 v[150:151], off
	v_lshl_add_u64 v[150:151], s[60:61], 0, v[144:145]
	s_add_i32 m0, s68, 0xe000
	s_nop 0
	global_load_lds_dwordx4 v[150:151], off
	s_waitcnt vmcnt(10)
	s_waitcnt lgkmcnt(0)
	s_barrier
	s_setprio 1
	s_waitcnt lgkmcnt(0)
	v_mfma_f32_16x16x32_bf16 v[124:127], v[146:149], v[204:207], 0
	v_mfma_f32_16x16x32_bf16 v[120:123], v[160:163], v[204:207], 0
	v_mfma_f32_16x16x32_bf16 v[108:111], v[146:149], v[212:215], 0
	v_mfma_f32_16x16x32_bf16 v[104:107], v[160:163], v[212:215], 0
	v_mfma_f32_16x16x32_bf16 v[92:95], v[146:149], v[220:223], 0
	v_mfma_f32_16x16x32_bf16 v[88:91], v[160:163], v[220:223], 0
	v_mfma_f32_16x16x32_bf16 v[76:79], v[146:149], v[228:231], 0
	v_mfma_f32_16x16x32_bf16 v[72:75], v[160:163], v[228:231], 0
	v_mfma_f32_16x16x32_bf16 v[124:127], v[156:159], v[208:211], v[124:127]
	v_mfma_f32_16x16x32_bf16 v[120:123], v[164:167], v[208:211], v[120:123]
	v_mfma_f32_16x16x32_bf16 v[108:111], v[156:159], v[216:219], v[108:111]
	v_mfma_f32_16x16x32_bf16 v[104:107], v[164:167], v[216:219], v[104:107]
	v_mfma_f32_16x16x32_bf16 v[92:95], v[156:159], v[224:227], v[92:95]
	v_mfma_f32_16x16x32_bf16 v[88:91], v[164:167], v[224:227], v[88:91]
	v_mfma_f32_16x16x32_bf16 v[76:79], v[156:159], v[232:235], v[76:79]
	v_mfma_f32_16x16x32_bf16 v[72:75], v[164:167], v[232:235], v[72:75]
	s_setprio 0
	s_setprio 1
	v_mfma_f32_16x16x32_bf16 v[116:119], v[168:171], v[204:207], 0
	v_mfma_f32_16x16x32_bf16 v[112:115], v[196:199], v[204:207], 0
	v_mfma_f32_16x16x32_bf16 v[100:103], v[168:171], v[212:215], 0
	v_mfma_f32_16x16x32_bf16 v[96:99], v[196:199], v[212:215], 0
	v_mfma_f32_16x16x32_bf16 v[84:87], v[168:171], v[220:223], 0
	v_mfma_f32_16x16x32_bf16 v[80:83], v[196:199], v[220:223], 0
	v_mfma_f32_16x16x32_bf16 v[68:71], v[168:171], v[228:231], 0
	v_mfma_f32_16x16x32_bf16 v[64:67], v[196:199], v[228:231], 0
	v_mfma_f32_16x16x32_bf16 v[116:119], v[192:195], v[208:211], v[116:119]
	v_mfma_f32_16x16x32_bf16 v[112:115], v[200:203], v[208:211], v[112:115]
	v_mfma_f32_16x16x32_bf16 v[100:103], v[192:195], v[216:219], v[100:103]
	v_mfma_f32_16x16x32_bf16 v[96:99], v[200:203], v[216:219], v[96:99]
	v_mfma_f32_16x16x32_bf16 v[84:87], v[192:195], v[224:227], v[84:87]
	v_mfma_f32_16x16x32_bf16 v[80:83], v[200:203], v[224:227], v[80:83]
	v_mfma_f32_16x16x32_bf16 v[68:71], v[192:195], v[232:235], v[68:71]
	v_mfma_f32_16x16x32_bf16 v[64:67], v[200:203], v[232:235], v[64:67]
	s_setprio 0
	s_barrier
	s_add_i32 s24, s47, s66
	v_lshl_add_u64 v[150:151], s[62:63], 0, v[132:133]
	s_mov_b32 m0, s24
	ds_read_b128 v[204:207], v155 offset:16384
	ds_read_b128 v[208:211], v155 offset:17408
	ds_read_b128 v[212:215], v155 offset:18432
	ds_read_b128 v[216:219], v155 offset:19456
	ds_read_b128 v[220:223], v155 offset:20480
	ds_read_b128 v[224:227], v155 offset:21504
	ds_read_b128 v[228:231], v155 offset:22528
	ds_read_b128 v[232:235], v155 offset:23552
	global_load_lds_dwordx4 v[150:151], off
	s_add_i32 m0, s24, 0x2000
	s_add_u32 s24, s62, 0x40000
	v_lshl_add_u64 v[236:237], s[62:63], 0, v[128:129]
	s_addc_u32 s25, s63, 0
	s_add_i32 s47, s50, s66
	global_load_lds_dwordx4 v[236:237], off
	v_lshl_add_u64 v[238:239], s[24:25], 0, v[132:133]
	s_mov_b32 m0, s47
	v_lshl_add_u64 v[240:241], s[64:65], 0, v[130:131]
	global_load_lds_dwordx4 v[238:239], off
	v_lshl_add_u64 v[238:239], s[24:25], 0, v[128:129]
	s_add_i32 m0, s47, 0x2000
	s_nop 0
	global_load_lds_dwordx4 v[238:239], off
	v_lshl_add_u64 v[238:239], s[64:65], 0, v[140:141]
	s_mov_b32 m0, s68
	s_nop 0
	global_load_lds_dwordx4 v[238:239], off
	s_mov_b32 m0, s69
	s_nop 0
	global_load_lds_dwordx4 v[240:241], off
	s_waitcnt vmcnt(16)
	s_waitcnt lgkmcnt(0)
	s_barrier
; #define PG8_STAGE(bufoff, gbase, voff) do { _Pragma("unroll") for (int _i = 0; _i < 2; ++_i) \
;         __builtin_amdgcn_global_load_lds((const unsigned*)((const char*)(gbase) + (voff)[_i]), (PG8_LAS unsigned*)(lds + (bufoff) + ldsw + _i * 8192), 16, 0, 0); } while (0)
; #define PG8_LDA(dst, b, h) do { _Pragma("unroll") for (int m = 0; m < 4; ++m) _Pragma("unroll") for (int k = 0; k < 2; ++k) dst[m][k] = *(const PG8_LAS bf16x8*)(lds + PG8_SA(b, h) + aoff + m * 2048 + k * 1024); } while (0)
; #define PG8_LDB(dst, b, h) do { _Pragma("unroll") for (int n = 0; n < 2; ++n) _Pragma("unroll") for (int k = 0; k < 2; ++k) dst[n][k] = *(const PG8_LAS bf16x8*)(lds + PG8_SB(b, h) + boff + n * 2048 + k * 1024); } while (0)
; #define PG8_MMA(ai, bj, At, Bt) do { __builtin_amdgcn_s_setprio(1); _Pragma("unroll") for (int m = 0; m < 4; ++m) _Pragma("unroll") for (int n = 0; n < 2; ++n) _Pragma("unroll") for (int k = 0; k < 2; ++k) \
;         acc[ai][bj][m][n] = __builtin_amdgcn_mfma_f32_16x16x32_bf16(Bt[n][k], At[m][k], acc[ai][bj][m][n], 0, 0, 0); __builtin_amdgcn_s_setprio(0); } while (0)
; #define PG8_WAIT_V(n) asm volatile("s_waitcnt vmcnt(" #n ")" ::: "memory")
; #define PG8_WAIT_L(n) asm volatile("s_waitcnt lgkmcnt(" #n ")" ::: "memory")
; #define PG8_BAR __builtin_amdgcn_s_barrier()
; #define PG8_SCHED __builtin_amdgcn_sched_barrier(0)
; template <class Epi, class Sched, bool ALIGN_EPI = false, bool SP2 = false>
; __device__ __forceinline__ void gemm_phase(PG8_LAS unsigned char* lds, const Gemm g, const Sched& S, const Epi& E) {
;     ...
;             PG8_WAIT_V(8); PG8_WAIT_L(0); PG8_BAR; PG8_MMA(1, 0, At, B0); PG8_MMA(1, 1, At, B1); PG8_BAR; PG8_SCHED;
;             PG8_LDB(B0, 1, 0); PG8_LDB(B1, 1, 1); PG8_SCHED; PG8_LDA(At, 1, 0); PG8_STAGE(PG8_SA(0, 1), a2 + hstep, voffA);
;             PG8_WAIT_V(8); PG8_WAIT_L(0); PG8_BAR; PG8_MMA(0, 0, At, B0); PG8_MMA(0, 1, At, B1); PG8_BAR; PG8_SCHED;
	s_setprio 1
	s_waitcnt lgkmcnt(0)
	v_mfma_f32_16x16x32_bf16 v[60:63], v[146:149], v[204:207], 0
	v_mfma_f32_16x16x32_bf16 v[56:59], v[160:163], v[204:207], 0
	v_mfma_f32_16x16x32_bf16 v[44:47], v[146:149], v[212:215], 0
	v_mfma_f32_16x16x32_bf16 v[40:43], v[160:163], v[212:215], 0
	v_mfma_f32_16x16x32_bf16 v[28:31], v[146:149], v[220:223], 0
	v_mfma_f32_16x16x32_bf16 v[24:27], v[160:163], v[220:223], 0
	v_mfma_f32_16x16x32_bf16 v[12:15], v[146:149], v[228:231], 0
	v_mfma_f32_16x16x32_bf16 v[8:11], v[160:163], v[228:231], 0
	v_mfma_f32_16x16x32_bf16 v[60:63], v[156:159], v[208:211], v[60:63]
	v_mfma_f32_16x16x32_bf16 v[56:59], v[164:167], v[208:211], v[56:59]
	v_mfma_f32_16x16x32_bf16 v[44:47], v[156:159], v[216:219], v[44:47]
	v_mfma_f32_16x16x32_bf16 v[40:43], v[164:167], v[216:219], v[40:43]
	v_mfma_f32_16x16x32_bf16 v[28:31], v[156:159], v[224:227], v[28:31]
	v_mfma_f32_16x16x32_bf16 v[24:27], v[164:167], v[224:227], v[24:27]
	v_mfma_f32_16x16x32_bf16 v[12:15], v[156:159], v[232:235], v[12:15]
	v_mfma_f32_16x16x32_bf16 v[8:11], v[164:167], v[232:235], v[8:11]
	s_setprio 0
	s_setprio 1
	v_mfma_f32_16x16x32_bf16 v[52:55], v[168:171], v[204:207], 0
	v_mfma_f32_16x16x32_bf16 v[48:51], v[196:199], v[204:207], 0
	v_mfma_f32_16x16x32_bf16 v[36:39], v[168:171], v[212:215], 0
	v_mfma_f32_16x16x32_bf16 v[32:35], v[196:199], v[212:215], 0
	v_mfma_f32_16x16x32_bf16 v[20:23], v[168:171], v[220:223], 0
	v_mfma_f32_16x16x32_bf16 v[16:19], v[196:199], v[220:223], 0
	v_mfma_f32_16x16x32_bf16 v[4:7], v[168:171], v[228:231], 0
	v_mfma_f32_16x16x32_bf16 v[0:3], v[196:199], v[228:231], 0
	v_mfma_f32_16x16x32_bf16 v[52:55], v[192:195], v[208:211], v[52:55]
	v_mfma_f32_16x16x32_bf16 v[48:51], v[200:203], v[208:211], v[48:51]
	v_mfma_f32_16x16x32_bf16 v[36:39], v[192:195], v[216:219], v[36:39]
	v_mfma_f32_16x16x32_bf16 v[32:35], v[200:203], v[216:219], v[32:35]
	v_mfma_f32_16x16x32_bf16 v[20:23], v[192:195], v[224:227], v[20:23]
	v_mfma_f32_16x16x32_bf16 v[16:19], v[200:203], v[224:227], v[16:19]
	v_mfma_f32_16x16x32_bf16 v[4:7], v[192:195], v[232:235], v[4:7]
	v_mfma_f32_16x16x32_bf16 v[0:3], v[200:203], v[232:235], v[0:3]
	s_setprio 0
	s_barrier
	s_add_i32 s47, 0, 0x18000
	s_add_i32 s50, 0, 0x1c000
	v_add_u32_e32 v164, s47, v153
	v_add_u32_e32 v184, s50, v153
	ds_read_b128 v[146:149], v164
	ds_read_b128 v[156:159], v164 offset:1024
	ds_read_b128 v[160:163], v164 offset:2048
	ds_read_b128 v[164:167], v164 offset:3072
	ds_read_b128 v[168:171], v184
	ds_read_b128 v[192:195], v184 offset:1024
	ds_read_b128 v[196:199], v184 offset:2048
	ds_read_b128 v[200:203], v184 offset:3072
	s_add_u32 s24, s64, 0x40000
	s_addc_u32 s25, s65, 0
	s_mov_b32 m0, s71
	v_lshl_add_u64 v[242:243], s[24:25], 0, v[140:141]
	ds_read_b128 v[204:207], v155 offset:32768
	ds_read_b128 v[208:211], v155 offset:33792
	ds_read_b128 v[212:215], v155 offset:34816
	ds_read_b128 v[216:219], v155 offset:35840
	ds_read_b128 v[220:223], v155 offset:36864
	ds_read_b128 v[224:227], v155 offset:37888
	ds_read_b128 v[228:231], v155 offset:38912
	ds_read_b128 v[232:235], v155 offset:39936
	global_load_lds_dwordx4 v[242:243], off
	v_lshl_add_u64 v[242:243], s[24:25], 0, v[130:131]
	s_mov_b32 m0, s87
	s_nop 0
	global_load_lds_dwordx4 v[242:243], off
	s_waitcnt vmcnt(8)
	s_waitcnt lgkmcnt(0)
	s_barrier
	s_setprio 1
	s_waitcnt lgkmcnt(0)
	v_mfma_f32_16x16x32_bf16 v[124:127], v[146:149], v[204:207], v[124:127]
	v_mfma_f32_16x16x32_bf16 v[120:123], v[160:163], v[204:207], v[120:123]
	v_mfma_f32_16x16x32_bf16 v[108:111], v[146:149], v[212:215], v[108:111]
	v_mfma_f32_16x16x32_bf16 v[104:107], v[160:163], v[212:215], v[104:107]
	v_mfma_f32_16x16x32_bf16 v[92:95], v[146:149], v[220:223], v[92:95]
	v_mfma_f32_16x16x32_bf16 v[88:91], v[160:163], v[220:223], v[88:91]
	v_mfma_f32_16x16x32_bf16 v[76:79], v[146:149], v[228:231], v[76:79]
	v_mfma_f32_16x16x32_bf16 v[72:75], v[160:163], v[228:231], v[72:75]
	v_mfma_f32_16x16x32_bf16 v[124:127], v[156:159], v[208:211], v[124:127]
	v_mfma_f32_16x16x32_bf16 v[120:123], v[164:167], v[208:211], v[120:123]
	v_mfma_f32_16x16x32_bf16 v[108:111], v[156:159], v[216:219], v[108:111]
	v_mfma_f32_16x16x32_bf16 v[104:107], v[164:167], v[216:219], v[104:107]
	v_mfma_f32_16x16x32_bf16 v[92:95], v[156:159], v[224:227], v[92:95]
	v_mfma_f32_16x16x32_bf16 v[88:91], v[164:167], v[224:227], v[88:91]
	v_mfma_f32_16x16x32_bf16 v[76:79], v[156:159], v[232:235], v[76:79]
	v_mfma_f32_16x16x32_bf16 v[72:75], v[164:167], v[232:235], v[72:75]
	s_setprio 0
	s_setprio 1
	v_mfma_f32_16x16x32_bf16 v[116:119], v[168:171], v[204:207], v[116:119]
	v_mfma_f32_16x16x32_bf16 v[112:115], v[196:199], v[204:207], v[112:115]
	v_mfma_f32_16x16x32_bf16 v[100:103], v[168:171], v[212:215], v[100:103]
	v_mfma_f32_16x16x32_bf16 v[96:99], v[196:199], v[212:215], v[96:99]
	v_mfma_f32_16x16x32_bf16 v[84:87], v[168:171], v[220:223], v[84:87]
	v_mfma_f32_16x16x32_bf16 v[80:83], v[196:199], v[220:223], v[80:83]
	v_mfma_f32_16x16x32_bf16 v[68:71], v[168:171], v[228:231], v[68:71]
	v_mfma_f32_16x16x32_bf16 v[64:67], v[196:199], v[228:231], v[64:67]
	v_mfma_f32_16x16x32_bf16 v[116:119], v[192:195], v[208:211], v[116:119]
	v_mfma_f32_16x16x32_bf16 v[112:115], v[200:203], v[208:211], v[112:115]
	v_mfma_f32_16x16x32_bf16 v[100:103], v[192:195], v[216:219], v[100:103]
	v_mfma_f32_16x16x32_bf16 v[96:99], v[200:203], v[216:219], v[96:99]
	v_mfma_f32_16x16x32_bf16 v[84:87], v[192:195], v[224:227], v[84:87]
	v_mfma_f32_16x16x32_bf16 v[80:83], v[200:203], v[224:227], v[80:83]
	v_mfma_f32_16x16x32_bf16 v[68:71], v[192:195], v[232:235], v[68:71]
	v_mfma_f32_16x16x32_bf16 v[64:67], v[200:203], v[232:235], v[64:67]
	s_setprio 0
	s_barrier
; #define PG8_STAGE(bufoff, gbase, voff) do { _Pragma("unroll") for (int _i = 0; _i < 2; ++_i) \
;         __builtin_amdgcn_global_load_lds((const unsigned*)((const char*)(gbase) + (voff)[_i]), (PG8_LAS unsigned*)(lds + (bufoff) + ldsw + _i * 8192), 16, 0, 0); } while (0)
; #define PG8_LDA(dst, b, h) do { _Pragma("unroll") for (int m = 0; m < 4; ++m) _Pragma("unroll") for (int k = 0; k < 2; ++k) dst[m][k] = *(const PG8_LAS bf16x8*)(lds + PG8_SA(b, h) + aoff + m * 2048 + k * 1024); } while (0)
; #define PG8_MMA(ai, bj, At, Bt) do { __builtin_amdgcn_s_setprio(1); _Pragma("unroll") for (int m = 0; m < 4; ++m) _Pragma("unroll") for (int n = 0; n < 2; ++n) _Pragma("unroll") for (int k = 0; k < 2; ++k) \
;         acc[ai][bj][m][n] = __builtin_amdgcn_mfma_f32_16x16x32_bf16(Bt[n][k], At[m][k], acc[ai][bj][m][n], 0, 0, 0); __builtin_amdgcn_s_setprio(0); } while (0)
; #define PG8_WAIT_V(n) asm volatile("s_waitcnt vmcnt(" #n ")" ::: "memory")
; #define PG8_WAIT_L(n) asm volatile("s_waitcnt lgkmcnt(" #n ")" ::: "memory")
; #define PG8_BAR __builtin_amdgcn_s_barrier()
; #define PG8_SCHED __builtin_amdgcn_sched_barrier(0)
; template <class Epi, class Sched, bool ALIGN_EPI = false, bool SP2 = false>
; __device__ __forceinline__ void gemm_phase(PG8_LAS unsigned char* lds, const Gemm g, const Sched& S, const Epi& E) {
;     ...
;         for (int t = 0; t < nt; t += 2) {
;     ...
;             PG8_LDA(At, 1, 1); PG8_STAGE(PG8_SB(1, 0), b3, voffB); PG8_STAGE(PG8_SB(1, 1), b3 + hstep, voffB); PG8_STAGE(PG8_SA(1, 0), a3, voffA);
;             PG8_WAIT_V(8); PG8_WAIT_L(0); PG8_BAR; PG8_MMA(1, 0, At, B0); PG8_MMA(1, 1, At, B1); PG8_BAR; PG8_SCHED;
	s_add_i32 s24, s47, s66
	v_lshl_add_u64 v[150:151], v[150:151], 0, s[14:15]
	s_mov_b32 m0, s24
	ds_read_b128 v[204:207], v155 offset:49152
	ds_read_b128 v[208:211], v155 offset:50176
	ds_read_b128 v[212:215], v155 offset:51200
	ds_read_b128 v[216:219], v155 offset:52224
	ds_read_b128 v[220:223], v155 offset:53248
	ds_read_b128 v[224:227], v155 offset:54272
	ds_read_b128 v[228:231], v155 offset:55296
	ds_read_b128 v[232:235], v155 offset:56320
	global_load_lds_dwordx4 v[150:151], off
	s_add_i32 m0, s24, 0x2000
	s_add_u32 s24, s62, 0x40080
	v_lshl_add_u64 v[150:151], v[236:237], 0, s[14:15]
	s_addc_u32 s25, s63, 0
	s_add_i32 s47, s50, s66
	global_load_lds_dwordx4 v[150:151], off
	v_lshl_add_u64 v[150:151], s[24:25], 0, v[132:133]
	s_mov_b32 m0, s47
	s_nop 0
	global_load_lds_dwordx4 v[150:151], off
	v_lshl_add_u64 v[150:151], s[24:25], 0, v[128:129]
	s_add_i32 m0, s47, 0x2000
	s_nop 0
	global_load_lds_dwordx4 v[150:151], off
	v_lshl_add_u64 v[150:151], v[238:239], 0, s[14:15]
	s_mov_b32 m0, s88
	s_nop 0
	global_load_lds_dwordx4 v[150:151], off
	v_lshl_add_u64 v[150:151], v[240:241], 0, s[14:15]
	s_mov_b32 m0, s89
	s_nop 0
	global_load_lds_dwordx4 v[150:151], off
	s_waitcnt vmcnt(8)
	s_waitcnt lgkmcnt(0)
	s_barrier
	s_setprio 1
	s_waitcnt lgkmcnt(0)
	v_mfma_f32_16x16x32_bf16 v[60:63], v[146:149], v[204:207], v[60:63]
	v_mfma_f32_16x16x32_bf16 v[56:59], v[160:163], v[204:207], v[56:59]
	v_mfma_f32_16x16x32_bf16 v[44:47], v[146:149], v[212:215], v[44:47]
	v_mfma_f32_16x16x32_bf16 v[40:43], v[160:163], v[212:215], v[40:43]
	v_mfma_f32_16x16x32_bf16 v[28:31], v[146:149], v[220:223], v[28:31]
	v_mfma_f32_16x16x32_bf16 v[24:27], v[160:163], v[220:223], v[24:27]
	v_mfma_f32_16x16x32_bf16 v[12:15], v[146:149], v[228:231], v[12:15]
	v_mfma_f32_16x16x32_bf16 v[8:11], v[160:163], v[228:231], v[8:11]
	v_mfma_f32_16x16x32_bf16 v[60:63], v[156:159], v[208:211], v[60:63]
	v_mfma_f32_16x16x32_bf16 v[56:59], v[164:167], v[208:211], v[56:59]
	v_mfma_f32_16x16x32_bf16 v[44:47], v[156:159], v[216:219], v[44:47]
	v_mfma_f32_16x16x32_bf16 v[40:43], v[164:167], v[216:219], v[40:43]
	v_mfma_f32_16x16x32_bf16 v[28:31], v[156:159], v[224:227], v[28:31]
	v_mfma_f32_16x16x32_bf16 v[24:27], v[164:167], v[224:227], v[24:27]
	v_mfma_f32_16x16x32_bf16 v[12:15], v[156:159], v[232:235], v[12:15]
	v_mfma_f32_16x16x32_bf16 v[8:11], v[164:167], v[232:235], v[8:11]
	s_setprio 0
	s_setprio 1
	v_mfma_f32_16x16x32_bf16 v[52:55], v[168:171], v[204:207], v[52:55]
	v_mfma_f32_16x16x32_bf16 v[48:51], v[196:199], v[204:207], v[48:51]
	v_mfma_f32_16x16x32_bf16 v[36:39], v[168:171], v[212:215], v[36:39]
	v_mfma_f32_16x16x32_bf16 v[32:35], v[196:199], v[212:215], v[32:35]
	v_mfma_f32_16x16x32_bf16 v[20:23], v[168:171], v[220:223], v[20:23]
	v_mfma_f32_16x16x32_bf16 v[16:19], v[196:199], v[220:223], v[16:19]
	v_mfma_f32_16x16x32_bf16 v[4:7], v[168:171], v[228:231], v[4:7]
	v_mfma_f32_16x16x32_bf16 v[0:3], v[196:199], v[228:231], v[0:3]
	v_mfma_f32_16x16x32_bf16 v[52:55], v[192:195], v[208:211], v[52:55]
	v_mfma_f32_16x16x32_bf16 v[48:51], v[200:203], v[208:211], v[48:51]
	v_mfma_f32_16x16x32_bf16 v[36:39], v[192:195], v[216:219], v[36:39]
	v_mfma_f32_16x16x32_bf16 v[32:35], v[200:203], v[216:219], v[32:35]
	v_mfma_f32_16x16x32_bf16 v[20:23], v[192:195], v[224:227], v[20:23]
	v_mfma_f32_16x16x32_bf16 v[16:19], v[200:203], v[224:227], v[16:19]
	v_mfma_f32_16x16x32_bf16 v[4:7], v[192:195], v[232:235], v[4:7]
	v_mfma_f32_16x16x32_bf16 v[0:3], v[200:203], v[232:235], v[0:3]
	s_setprio 0
	s_barrier
	s_add_i32 s45, s45, 2
	s_add_u32 s60, s60, 0x100
	s_addc_u32 s61, s61, 0
	s_add_u32 s33, s33, 0x100
	s_addc_u32 s44, s44, 0
	s_cmp_gt_u32 s45, 13
